# NA work mapping: 8 waves = 1 head x 4 query groups x 2 consecutive grid rows (shared key rows requested concurrently), 16 head iterations, one row pair per CU
# speedup vs baseline: 1.0023x; 1.0023x over previous
; #define LAS __attribute__((address_space(3)))
; __device__ __forceinline__ void na_phase(const Frame& F, const bf16* QH, const bf16* VB, const float* rpb, bf16* U) {
;     const bf16* KH = QH + (size_t)16 * MTOK * 64;
;     LAS float* RP = (LAS float*)F.lds;
;     for (int i = F.tid; i < 16 * 465; i += 512) RP[i] = rpb[i];
;     __syncthreads();
;     const int lane = F.lane, n = lane & 15, q4 = lane >> 4;
;     const int vcu = (F.G % 8 == 0) ? (F.bid % 8) * (F.G / 8) + F.bid / 8 : F.bid;
;     for (int br = vcu; br < MB * 256; br += F.G) {
;         const int b = br >> 8, r = br & 255;
;         const int rs = min(max(r - 4, 0), 248);
; #pragma unroll 1
;         for (int it = 0; it < 8; ++it) {
;             const int hj = it * 8 + F.wave, h = hj >> 2, j = hj & 3;
;             const int c0 = (j == 0) ? 0 : (j == 1) ? 8 : (j == 2) ? 24 : 32;
;             const int qcol = 16 * j + n, cs = min(max(qcol - 8, 0), 48);
;             const size_t tokq = (size_t)b * SEQL + r * 64 + qcol;
.LBB0_899:
	s_cmp_lt_i32 s72, 10
	s_cselect_b64 s[4:5], -1, 0
	s_and_b64 s[36:37], s[4:5], s[0:1]
	s_andn2_b64 vcc, exec, s[36:37]
	s_cbranch_vccnz .LBB0_913
	v_lshlrev_b32_e32 v4, 2, v221
	v_add_u32_e32 v3, 0, v4
	s_waitcnt lgkmcnt(0)
	v_add_u32_e32 v6, 0x1000, v4
	v_add_u32_e32 v7, 0x2000, v4
	v_add_u32_e32 v8, 0x3000, v4
	v_add_u32_e32 v9, 0x4000, v4
	v_add_u32_e32 v26, 0x5000, v4
	v_add_u32_e32 v27, 0x6000, v4
	v_add_u32_e32 v28, 0x7000, v4
	global_load_dword v10, v4, s[24:25]
	global_load_dword v11, v4, s[24:25] offset:2048
	global_load_dword v12, v6, s[24:25]
	global_load_dword v13, v6, s[24:25] offset:2048
	global_load_dword v14, v7, s[24:25]
	global_load_dword v15, v7, s[24:25] offset:2048
	global_load_dword v16, v8, s[24:25]
	global_load_dword v17, v8, s[24:25] offset:2048
	global_load_dword v18, v9, s[24:25]
	global_load_dword v19, v9, s[24:25] offset:2048
	global_load_dword v20, v26, s[24:25]
	global_load_dword v21, v26, s[24:25] offset:2048
	global_load_dword v22, v27, s[24:25]
	global_load_dword v23, v27, s[24:25] offset:2048
	v_cmp_gt_u32_e32 vcc, 0x110, v221
	s_nop 1
	s_and_saveexec_b64 s[0:1], vcc
	global_load_dword v24, v28, s[24:25]
	s_mov_b64 exec, s[0:1]
	s_waitcnt vmcnt(0)
	ds_write_b32 v3, v10
	ds_write_b32 v3, v11 offset:2048
	ds_write_b32 v3, v12 offset:4096
	ds_write_b32 v3, v13 offset:6144
	ds_write_b32 v3, v14 offset:8192
	ds_write_b32 v3, v15 offset:10240
	ds_write_b32 v3, v16 offset:12288
	ds_write_b32 v3, v17 offset:14336
	ds_write_b32 v3, v18 offset:16384
	ds_write_b32 v3, v19 offset:18432
	ds_write_b32 v3, v20 offset:20480
	ds_write_b32 v3, v21 offset:22528
	ds_write_b32 v3, v22 offset:24576
	ds_write_b32 v3, v23 offset:26624
	s_and_saveexec_b64 s[0:1], vcc
	ds_write_b32 v3, v24 offset:28672
	s_mov_b64 exec, s[0:1]
	s_ashr_i32 s1, s2, 31
	s_lshr_b32 s1, s1, 29
	s_add_i32 s1, s2, s1
	s_ashr_i32 s3, s1, 3
	s_and_b32 s1, s1, -8
	s_sub_i32 s1, s2, s1
	s_ashr_i32 s4, s74, 3
	s_mul_i32 s1, s4, s1
	s_and_b32 s0, s74, 7
	s_add_i32 s1, s1, s3
	s_cmp_eq_u32 s0, 0
	s_cselect_b32 s3, s1, s2
	s_mov_b32 s47, 0
	s_lshr_b32 s1, s3, 7
	s_and_b32 s3, s3, 0x7f
	s_lshl_b32 s3, s3, 1
	s_lshl_b32 s1, s1, 8
	s_or_b32 s3, s3, s1
	s_cmpk_lt_i32 s3, 0x200
	s_waitcnt lgkmcnt(0)
	s_barrier
	s_cbranch_scc0 .LBB0_912
	v_mbcnt_lo_u32_b32 v3, -1, 0
	v_readlane_b32 s0, v248, 14
	v_mbcnt_hi_u32_b32 v3, -1, v3
	s_bfe_u32 s6, s0, 0x20006
	v_and_b32_e32 v5, 64, v3
	s_lshl_b32 s8, s6, 4
	v_xor_b32_e32 v4, 16, v3
	v_add_u32_e32 v5, 64, v5
	s_cmp_eq_u32 s6, 2
	v_cmp_lt_i32_e32 vcc, v4, v5
	v_and_b32_e32 v0, 15, v221
	v_lshrrev_b32_e32 v72, 4, v220
	s_cselect_b32 s7, 24, 32
	v_cndmask_b32_e32 v4, v3, v4, vcc
	s_lshr_b32 s88, s0, 8
	s_mov_b32 s46, 0
	v_or_b32_e32 v1, s8, v0
	v_lshlrev_b32_e32 v48, 3, v72
	v_lshlrev_b32_e32 v73, 2, v4
	v_xor_b32_e32 v4, 32, v3
	s_lshl_b64 s[0:1], s[46:47], 22
	v_sub_u32_e64 v1, v1, 8 clamp
	v_cmp_lt_i32_e32 vcc, v4, v5
	v_lshl_or_b32 v52, v0, 4, s0
	v_mov_b32_e32 v53, s1
	v_add_u32_e32 v75, s8, v0
	v_sub_u32_e32 v0, v48, v0
	s_mul_i32 s1, s46, 0x744
	v_min_u32_e32 v49, 48, v1
	v_mov_b32_e32 v51, 0
	v_lshlrev_b32_e32 v1, 1, v221
	v_and_b32_e32 v2, 3, v221
	v_cndmask_b32_e32 v3, v3, v4, vcc
	v_lshl_or_b32 v50, s46, 7, v48
	s_mov_b64 s[4:5], 0x8000040
	v_subrev_u32_e32 v76, s8, v0
	s_add_i32 s33, s1, 0
	v_add_u32_e32 v57, 16, v49
	v_lshlrev_b32_e32 v74, 2, v3
	v_lshl_add_u64 v[54:55], v[50:51], 0, s[4:5]
	s_addk_i32 s33, 0x364
	v_and_or_b32 v56, v1, 24, v2
	s_cmp_eq_u32 s6, 0
	s_cselect_b32 s98, 0, s7
	s_cmp_eq_u32 s6, 1
	s_cselect_b32 s98, 8, s98
	s_lshl_b32 s98, s98, 3
	v_and_b32_e32 v252, 15, v221
	v_lshrrev_b32_e32 v253, 2, v252
	v_and_b32_e32 v254, 3, v252
	v_lshlrev_b32_e32 v249, 10, v72
	v_lshl_or_b32 v250, v254, 4, v249
	v_lshl_or_b32 v249, v253, 6, v250
	v_add_u32_e32 v249, s98, v249
	v_and_b32_e32 v254, 1, v253
	v_lshl_or_b32 v250, v254, 9, v250
	v_lshrrev_b32_e32 v254, 3, v252
	v_lshl_add_u32 v254, s6, 1, v254
	v_lshl_or_b32 v250, v254, 6, v250
	v_mov_b32_e32 v58, s0
	s_mov_b64 s[90:91], -1
	s_mov_b64 s[92:93], -1
	s_mov_b64 s[98:99], 0
	s_cmp_eq_u32 s6, 0
	s_cselect_b32 s90, 0x0fff0fff, s90
	s_cselect_b32 s91, 0x0fff0fff, s91
	s_cselect_b32 s93, 0x0000ffff, s93
	s_cselect_b32 s99, 0xffff0000, s99
	s_cmp_eq_u32 s6, 3
	s_cselect_b32 s90, 0xfff0fff0, s90
	s_cselect_b32 s91, 0xfff0fff0, s91
	s_cselect_b32 s92, 0xffff0000, s92
	s_cselect_b32 s98, 0x0000ffff, s98
	v_mov_b32_e32 v59, v53
	v_add_u32_e32 v77, 1, v76
	v_add_u32_e32 v78, 2, v76
	v_add_u32_e32 v79, 3, v76
	v_add_u32_e32 v80, 4, v76
	v_add_u32_e32 v81, 5, v76
	v_add_u32_e32 v82, 6, v76
	v_add_u32_e32 v83, 7, v76
	s_movk_i32 s52, 0x7c
	s_brev_b32 s53, 8
	s_mov_b32 s54, 0x10200000
	s_mov_b32 s55, 0x10001000
	s_mov_b32 s56, 0x10201000
	s_mov_b32 s57, 0x10002000
	s_mov_b32 s58, 0x10202000
	s_mov_b32 s59, 0x10003000
	s_mov_b32 s60, 0x10203000
	s_mov_b32 s61, 0x10004000
	s_mov_b32 s62, 0x10204000
	s_mov_b32 s63, 0x10005000
	s_mov_b32 s64, 0x10205000
	s_mov_b32 s65, 0x10006000
	s_mov_b32 s66, 0x10206000
	s_mov_b32 s67, 0x10007000
	s_mov_b32 s76, 0x10207000
	s_mov_b32 s77, 0xff61b1e6
	v_mov_b32_e32 v84, 0xff61b1e6
	s_brev_b32 s78, 40
	s_mov_b32 s79, 0x14002000
	s_mov_b32 s80, 0x14004000
	s_mov_b32 s81, 0x14006000
	s_mov_b32 s82, 0x14008000
	s_mov_b32 s83, 0x1400a000
	s_mov_b32 s84, 0x1400c000
	s_mov_b32 s85, 0x1400e000
	s_mov_b64 s[48:49], 0x400000
	s_mov_b64 s[50:51], 0x80
	s_mov_b32 s86, s3
	s_branch .LBB0_905
.LBB0_904:
	s_addk_i32 s3, 0x200
	s_addk_i32 s86, 0x200
	s_cmpk_gt_i32 s3, 0x1ff
	s_cbranch_scc1 .LBB0_912
; __device__ __forceinline__ void na_phase(const Frame& F, const bf16* QH, const bf16* VB, const float* rpb, bf16* U) {
;     ...
;     for (int br = vcu; br < MB * 256; br += F.G) {
;         const int b = br >> 8, r = br & 255;
;         const int rs = min(max(r - 4, 0), 248);
; #pragma unroll 1
;         for (int it = 0; it < 8; ++it) {
;             const int hj = it * 8 + F.wave, h = hj >> 2, j = hj & 3;
;             const int c0 = (j == 0) ? 0 : (j == 1) ? 8 : (j == 2) ? 24 : 32;
;             const int qcol = 16 * j + n, cs = min(max(qcol - 8, 0), 48);
;             const size_t tokq = (size_t)b * SEQL + r * 64 + qcol;
;             bf16x8 qf[2];
; #pragma unroll
;             for (int ks = 0; ks < 2; ++ks) qf[ks] = *(const bf16x8*)(QH + (((size_t)h * 2 + ks) * MTOK + tokq) * 32 + q4 * 8);
;             f32x4 acc[16];
; #pragma unroll
;             for (int blk = 0; blk < 16; ++blk) { const int i = blk >> 1, hf = blk & 1;
;                 const size_t tokk = (size_t)b * SEQL + (rs + i) * 64 + c0 + 8 * (n >> 2) + 4 * hf + (n & 3);
;                 const bf16* kp = KH + ((size_t)h * 2 * MTOK + tokk) * 32 + q4 * 8; const bf16x8 k0 = *(const bf16x8*)kp, k1 = *(const bf16x8*)(kp + (size_t)MTOK * 32);
;                 f32x4 a = (f32x4){0.f, 0.f, 0.f, 0.f};
;                 a = __builtin_amdgcn_mfma_f32_16x16x32_bf16(k0, qf[0], a, 0, 0, 0);
;                 a = __builtin_amdgcn_mfma_f32_16x16x32_bf16(k1, qf[1], a, 0, 0, 0);
;                 acc[blk] = a; }
.LBB0_905:
	s_and_b32 s8, s86, 0xff
	s_add_i32 s8, s8, s88
	v_sub_u32_e64 v0, s8, 4 clamp
	v_lshl_add_u32 v1, s8, 6, v75
	v_lshl_add_u32 v251, s8, 12, v250
	v_readfirstlane_b32 s0, v0
	s_cmpk_lt_u32 s0, 0xf8
	s_cselect_b32 s1, 0, 0
	s_cselect_b32 s0, s0, 0xf8
	s_and_b32 s4, s3, 0xffffff00
	s_ashr_i32 s5, s4, 31
	s_or_b64 s[4:5], s[0:1], s[4:5]
	s_lshl_b64 s[4:5], s[4:5], 13
	v_lshl_add_u64 v[60:61], v[52:53], 0, s[4:5]
	s_ashr_i32 s4, s3, 8
	v_min_u32_e32 v0, 0xf8, v0
	s_ashr_i32 s5, s4, 31
	v_mul_lo_u32 v0, v0, s52
	s_mulk_i32 s8, 0x7c
	s_lshl_b64 s[10:11], s[4:5], 25
	v_lshlrev_b32_e32 v50, 11, v1
	v_subrev_u32_e32 v0, s8, v0
	s_lshl_b64 s[8:9], s[4:5], 14
	v_lshl_add_u64 v[2:3], v[54:55], 0, s[10:11]
	v_lshl_add_u64 v[62:63], v[2:3], 0, v[50:51]
	v_mov_b32_e32 v2, s8
	s_lshl_b32 s46, s0, 12
	v_lshl_or_b32 v64, s0, 6, v2
	s_lshl_b64 s[0:1], s[4:5], 20
	v_add_u32_e32 v85, s33, v0
	v_mov_b32_e32 v0, v251
	v_mov_b32_e32 v1, v51
	v_lshl_add_u64 v[2:3], v[58:59], 0, s[0:1]
	v_mov_b32_e32 v65, s9
	v_lshl_add_u64 v[66:67], v[2:3], 0, s[46:47]
	v_lshl_add_u64 v[68:69], v[2:3], 0, v[0:1]
	v_mov_b64_e32 v[70:71], v[58:59]
	v_add_u32_e32 v70, v249, v70
	v_add_u32_e32 v66, v249, v66
	s_mov_b32 s87, s47
	s_branch .LBB0_907
.LBB0_906:
	v_lshl_add_u64 v[0:1], s[70:71], 0, v[68:69]
	v_add_co_u32_e32 v2, vcc, 0xc000000, v0
	v_mov_b32_e32 v50, 0
	s_nop 0
	v_addc_co_u32_e32 v3, vcc, 0, v1, vcc
	v_add_co_u32_e32 v4, vcc, 0xc200000, v0
	v_lshl_add_u64 v[68:69], v[68:69], 0, s[48:49]
	s_nop 0
	v_addc_co_u32_e32 v5, vcc, 0, v1, vcc
	global_load_dwordx4 v[0:3], v[2:3], off
	s_nop 0
	global_load_dwordx4 v[86:89], v[4:5], off
	v_lshl_add_u64 v[4:5], v[64:65], 0, 0
	v_lshlrev_b64 v[4:5], 6, v[4:5]
	v_lshl_add_u64 v[4:5], v[70:71], 0, v[4:5]
	v_lshl_add_u64 v[4:5], s[70:71], 0, v[4:5]
	v_add_co_u32_e32 v8, vcc, 0x10000000, v4
	v_lshl_add_u64 v[70:71], v[70:71], 0, s[48:49]
	s_nop 0
	v_addc_co_u32_e32 v9, vcc, 0, v5, vcc
	v_add_co_u32_e32 v12, vcc, 0x10200000, v4
	s_nop 1
	v_addc_co_u32_e32 v13, vcc, 0, v5, vcc
	v_lshl_add_u64 v[4:5], v[66:67], 0, v[50:51]
	v_lshl_add_u64 v[114:115], s[70:71], 0, v[4:5]
	v_add_co_u32_e32 v106, vcc, s61, v114
	v_add_u32_e32 v50, s46, v48
	s_nop 0
	v_addc_co_u32_e32 v107, vcc, 0, v115, vcc
	v_add_co_u32_e32 v16, vcc, s53, v114
	s_mov_b64 exec, s[90:91]
	global_load_dwordx4 v[4:7], v[106:107], off offset:-4096
	s_mov_b64 exec, -1
	s_nop 0
	s_mov_b64 exec, s[90:91]
	global_load_dwordx4 v[8:11], v[8:9], off
	s_mov_b64 exec, -1
	s_nop 0
	s_mov_b64 exec, s[90:91]
	global_load_dwordx4 v[12:15], v[12:13], off
	s_mov_b64 exec, -1
	v_addc_co_u32_e32 v17, vcc, 0, v115, vcc
	v_add_co_u32_e32 v28, vcc, s54, v114
	s_mov_b64 s[0:1], vcc
	v_add_co_u32_e32 v20, vcc, s55, v114
	s_mov_b64 exec, s[90:91]
	global_load_dwordx4 v[16:19], v[16:17], off offset:512
	s_mov_b64 exec, -1
	s_nop 0
	v_addc_co_u32_e32 v21, vcc, 0, v115, vcc
	s_mov_b64 exec, s[90:91]
	global_load_dwordx4 v[20:23], v[20:21], off offset:512
	s_mov_b64 exec, -1
	s_nop 0
	s_mov_b64 exec, s[90:91]
	global_load_dwordx4 v[24:27], v[106:107], off
	s_mov_b64 exec, -1
	v_addc_co_u32_e64 v29, vcc, 0, v115, s[0:1]
	v_add_co_u32_e32 v36, vcc, s57, v114
	s_mov_b64 exec, s[90:91]
	global_load_dwordx4 v[28:31], v[28:29], off offset:512
	s_mov_b64 exec, -1
	s_nop 0
	v_addc_co_u32_e32 v37, vcc, 0, v115, vcc
	v_add_co_u32_e32 v38, vcc, s56, v114
	s_mov_b64 exec, s[90:91]
	global_load_dwordx4 v[32:35], v[36:37], off offset:-4096
	s_mov_b64 exec, -1
	s_nop 0
	v_addc_co_u32_e32 v39, vcc, 0, v115, vcc
	v_add_co_u32_e32 v40, vcc, s58, v114
	v_cmp_lt_u32_e64 s[0:1], v50, v57
	s_nop 0
	v_addc_co_u32_e32 v41, vcc, 0, v115, vcc
	v_add_co_u32_e32 v108, vcc, s62, v114
	v_lshl_add_u64 v[66:67], v[66:67], 0, s[48:49]
	s_nop 0
	v_addc_co_u32_e32 v109, vcc, 0, v115, vcc
	s_waitcnt vmcnt(7)
	v_mfma_f32_16x16x32_bf16 v[4:7], v[4:7], v[0:3], 0
	s_waitcnt vmcnt(6)
	v_mfma_f32_16x16x32_bf16 v[8:11], v[8:11], v[0:3], 0
	s_waitcnt vmcnt(5)
	v_mfma_f32_16x16x32_bf16 v[90:93], v[12:15], v[86:89], v[8:11]
	s_waitcnt vmcnt(3)
	v_mfma_f32_16x16x32_bf16 v[12:15], v[20:23], v[0:3], 0
	s_nop 3
	s_mov_b64 exec, s[90:91]
	global_load_dwordx4 v[8:11], v[38:39], off offset:512
	s_mov_b64 exec, -1
	s_mov_b64 exec, s[90:91]
	global_load_dwordx4 v[20:23], v[36:37], off
	s_mov_b64 exec, -1
	s_nop 0
	s_mov_b64 exec, s[90:91]
	global_load_dwordx4 v[36:39], v[36:37], off offset:512
	s_mov_b64 exec, -1
	s_nop 1
	v_mfma_f32_16x16x32_bf16 v[16:19], v[16:19], v[0:3], 0
	s_waitcnt vmcnt(4)
	v_mfma_f32_16x16x32_bf16 v[94:97], v[28:31], v[86:89], v[16:19]
	s_nop 5
	s_mov_b64 exec, s[90:91]
	global_load_dwordx4 v[16:19], v[40:41], off offset:-4096
	s_mov_b64 exec, -1
	s_waitcnt vmcnt(4)
	v_mfma_f32_16x16x32_bf16 v[32:35], v[32:35], v[0:3], 0
	s_waitcnt vmcnt(3)
	v_mfma_f32_16x16x32_bf16 v[98:101], v[8:11], v[86:89], v[12:15]
	s_nop 2
	v_add_co_u32_e32 v12, vcc, s59, v114
	s_waitcnt vmcnt(1)
	v_mfma_f32_16x16x32_bf16 v[28:31], v[36:39], v[0:3], 0
	s_mov_b64 exec, s[90:91]
	global_load_dwordx4 v[36:39], v[40:41], off
	s_mov_b64 exec, -1
	s_nop 0
	s_mov_b64 exec, s[90:91]
	global_load_dwordx4 v[40:43], v[40:41], off offset:512
	s_mov_b64 exec, -1
	v_addc_co_u32_e32 v13, vcc, 0, v115, vcc
	s_mov_b64 exec, s[90:91]
	global_load_dwordx4 v[8:11], v[108:109], off offset:-4096
	s_mov_b64 exec, -1
	s_nop 1
	v_mfma_f32_16x16x32_bf16 v[20:23], v[20:23], v[0:3], 0
	s_mov_b64 exec, s[90:91]
	global_load_dwordx4 v[12:15], v[12:13], off offset:512
	s_mov_b64 exec, -1
	s_waitcnt vmcnt(4)
	v_mfma_f32_16x16x32_bf16 v[102:105], v[16:19], v[86:89], v[32:35]
	s_mov_b64 exec, s[90:91]
	global_load_dwordx4 v[16:19], v[106:107], off offset:512
	s_mov_b64 exec, -1
	s_waitcnt vmcnt(4)
; #define LAS __attribute__((address_space(3)))
; __device__ __forceinline__ void na_phase(const Frame& F, const bf16* QH, const bf16* VB, const float* rpb, bf16* U) {
;     ...
; #pragma unroll
;             for (int blk = 0; blk < 16; ++blk) { const int i = blk >> 1, hf = blk & 1;
;                 const size_t tokk = (size_t)b * SEQL + (rs + i) * 64 + c0 + 8 * (n >> 2) + 4 * hf + (n & 3);
;                 const bf16* kp = KH + ((size_t)h * 2 * MTOK + tokk) * 32 + q4 * 8; const bf16x8 k0 = *(const bf16x8*)kp, k1 = *(const bf16x8*)(kp + (size_t)MTOK * 32);
;                 f32x4 a = (f32x4){0.f, 0.f, 0.f, 0.f};
;                 a = __builtin_amdgcn_mfma_f32_16x16x32_bf16(k0, qf[0], a, 0, 0, 0);
;                 a = __builtin_amdgcn_mfma_f32_16x16x32_bf16(k1, qf[1], a, 0, 0, 0);
;                 acc[blk] = a; }
;             float mx = -3.0e38f;
;             int cofs[8]; bool okk[8];
; #pragma unroll
;             for (int k8 = 0; k8 < 8; ++k8) { const int kc = c0 + 8 * q4 + 4 * (k8 >> 2) + (k8 & 3); okk[k8] = (kc >= cs) && (kc < cs + 16); cofs[k8] = min(max(kc - qcol + 15, 0), 30); }
; #pragma unroll
;             for (int i = 0; i < 8; ++i) { const LAS float* rprow = RP + (h * 15 + (rs + i - r + 7)) * 31;
; #pragma unroll
;                 for (int k8 = 0; k8 < 8; ++k8) { const int blk = 2 * i + (k8 >> 2), e = k8 & 3;
;                     const float bia = rprow[cofs[k8]];
;                     const float sb = acc[blk][e] * 0.125f + bia; const float s = okk[k8] ? sb : -3.0e38f;
	v_mfma_f32_16x16x32_bf16 v[44:47], v[36:39], v[86:89], v[20:23]
	s_nop 2
	v_add_co_u32_e32 v20, vcc, s60, v114
	s_nop 1
	v_addc_co_u32_e32 v21, vcc, 0, v115, vcc
	s_waitcnt vmcnt(2)
	v_mfma_f32_16x16x32_bf16 v[36:39], v[8:11], v[86:89], v[4:7]
	s_nop 2
	s_mov_b64 exec, s[90:91]
	global_load_dwordx4 v[4:7], v[20:21], off offset:512
	s_mov_b64 exec, -1
	s_waitcnt vmcnt(2)
	v_mfma_f32_16x16x32_bf16 v[8:11], v[12:15], v[0:3], 0
	v_mfma_f32_16x16x32_bf16 v[40:43], v[40:43], v[86:89], v[28:31]
	s_nop 2
	v_add_co_u32_e32 v28, vcc, s65, v114
	s_waitcnt vmcnt(0)
	v_mfma_f32_16x16x32_bf16 v[32:35], v[4:7], v[86:89], v[8:11]
	s_nop 2
	s_mov_b64 exec, s[90:91]
	global_load_dwordx4 v[8:11], v[108:109], off
	s_mov_b64 exec, -1
	s_mov_b64 exec, s[90:91]
	global_load_dwordx4 v[12:15], v[108:109], off offset:512
	s_mov_b64 exec, -1
	v_addc_co_u32_e32 v29, vcc, 0, v115, vcc
	v_mfma_f32_16x16x32_bf16 v[4:7], v[24:27], v[0:3], 0
	v_add_co_u32_e32 v110, vcc, s66, v114
	s_mov_b64 exec, s[90:91]
	global_load_dwordx4 v[106:109], v[28:29], off offset:512
	s_mov_b64 exec, -1
	s_waitcnt vmcnt(2)
	v_mfma_f32_16x16x32_bf16 v[20:23], v[8:11], v[86:89], v[4:7]
	s_nop 3
	s_mov_b64 exec, s[90:91]
	global_load_dwordx4 v[4:7], v[28:29], off offset:-4096
	s_mov_b64 exec, -1
	v_addc_co_u32_e32 v111, vcc, 0, v115, vcc
	v_mfma_f32_16x16x32_bf16 v[8:11], v[16:19], v[0:3], 0
	s_mov_b64 exec, s[90:91]
	global_load_dwordx4 v[16:19], v[110:111], off offset:-4096
	s_mov_b64 exec, -1
	s_waitcnt vmcnt(3)
	v_mfma_f32_16x16x32_bf16 v[24:27], v[12:15], v[86:89], v[8:11]
	v_add_co_u32_e32 v12, vcc, s63, v114
	s_nop 1
	v_addc_co_u32_e32 v13, vcc, 0, v115, vcc
	s_mov_b64 exec, s[90:91]
	global_load_dwordx4 v[12:15], v[12:13], off offset:512
	s_mov_b64 exec, -1
	v_add_co_u32_e32 v112, vcc, s64, v114
	s_mov_b64 exec, s[90:91]
	global_load_dwordx4 v[8:11], v[28:29], off
	s_mov_b64 exec, -1
	s_nop 0
	v_addc_co_u32_e32 v113, vcc, 0, v115, vcc
	v_add_co_u32_e32 v116, vcc, s67, v114
	s_waitcnt vmcnt(3)
	v_mfma_f32_16x16x32_bf16 v[4:7], v[4:7], v[0:3], 0
	v_addc_co_u32_e32 v117, vcc, 0, v115, vcc
	v_add_co_u32_e32 v114, vcc, s76, v114
	s_waitcnt vmcnt(2)
	v_mfma_f32_16x16x32_bf16 v[28:31], v[16:19], v[86:89], v[4:7]
	v_addc_co_u32_e32 v115, vcc, 0, v115, vcc
	v_cmp_ge_u32_e32 vcc, v50, v49
	s_nop 1
	s_mov_b64 exec, s[90:91]
	global_load_dwordx4 v[4:7], v[112:113], off offset:512
	s_mov_b64 exec, -1
	s_waitcnt vmcnt(2)
	v_mfma_f32_16x16x32_bf16 v[12:15], v[12:15], v[0:3], 0
	s_and_b64 vcc, vcc, s[0:1]
	s_waitcnt vmcnt(0)
	v_mfma_f32_16x16x32_bf16 v[16:19], v[4:7], v[86:89], v[12:15]
	v_mfma_f32_16x16x32_bf16 v[4:7], v[8:11], v[0:3], 0
	s_mov_b64 exec, s[90:91]
	global_load_dwordx4 v[8:11], v[110:111], off
	s_mov_b64 exec, -1
	s_nop 0
	s_mov_b64 exec, s[90:91]
	global_load_dwordx4 v[110:113], v[110:111], off offset:512
	s_mov_b64 exec, -1
	s_waitcnt vmcnt(1)
	v_mfma_f32_16x16x32_bf16 v[12:15], v[8:11], v[86:89], v[4:7]
	s_nop 2
	s_mov_b64 exec, s[90:91]
	global_load_dwordx4 v[4:7], v[116:117], off
	s_mov_b64 exec, -1
	s_nop 1
	v_mfma_f32_16x16x32_bf16 v[8:11], v[106:109], v[0:3], 0
	s_mov_b64 exec, s[90:91]
	global_load_dwordx4 v[106:109], v[114:115], off
	s_mov_b64 exec, -1
	s_waitcnt vmcnt(2)
	v_mfma_f32_16x16x32_bf16 v[8:11], v[110:113], v[86:89], v[8:11]
	s_mov_b64 exec, s[90:91]
	global_load_dwordx4 v[110:113], v[116:117], off offset:512
	s_mov_b64 exec, -1
	s_nop 0
	s_mov_b64 exec, s[90:91]
	global_load_dwordx4 v[114:117], v[114:115], off offset:512
	s_mov_b64 exec, -1
	s_waitcnt vmcnt(3)
	v_mfma_f32_16x16x32_bf16 v[4:7], v[4:7], v[0:3], 0
	s_waitcnt vmcnt(1)
	v_mfma_f32_16x16x32_bf16 v[0:3], v[110:113], v[0:3], 0
	v_add_u32_e32 v110, s87, v85
	s_addk_i32 s87, 0x744
	v_mfma_f32_16x16x32_bf16 v[4:7], v[106:109], v[86:89], v[4:7]
	s_waitcnt vmcnt(0)
	v_mfma_f32_16x16x32_bf16 v[0:3], v[114:117], v[86:89], v[0:3]
	v_or_b32_e32 v86, 1, v50
	v_cmp_ge_u32_e64 s[4:5], v86, v49
	v_cmp_lt_u32_e64 s[8:9], v86, v57
	v_or_b32_e32 v86, 2, v50
	v_cmp_ge_u32_e64 s[10:11], v86, v49
	v_cmp_lt_u32_e64 s[12:13], v86, v57
	v_or_b32_e32 v86, 3, v50
	v_cmp_ge_u32_e64 s[14:15], v86, v49
	v_cmp_lt_u32_e64 s[16:17], v86, v57
	v_or_b32_e32 v86, 4, v50
	v_cmp_ge_u32_e64 s[18:19], v86, v49
	v_cmp_lt_u32_e64 s[20:21], v86, v57
	v_or_b32_e32 v86, 5, v50
	v_cmp_ge_u32_e64 s[22:23], v86, v49
	v_cmp_lt_u32_e64 s[24:25], v86, v57
	v_or_b32_e32 v86, 6, v50
	v_cmp_ge_u32_e64 s[26:27], v86, v49
	v_cmp_lt_u32_e64 s[28:29], v86, v57
	v_add_u32_e32 v86, s46, v76
	v_add_u32_e32 v88, s46, v77
	v_max_i32_e32 v86, -15, v86
	v_max_i32_e32 v88, -15, v88
	v_add_u32_e32 v86, 15, v86
	v_add_u32_e32 v88, 15, v88
	v_min_u32_e32 v86, 30, v86
	v_min_u32_e32 v88, 30, v88
	v_lshl_add_u32 v112, v86, 2, v110
	v_lshl_add_u32 v113, v88, 2, v110
	ds_read2_b32 v[86:87], v112 offset1:31
	ds_read2_b32 v[88:89], v113 offset1:31
	v_or_b32_e32 v50, 7, v50
	v_cmp_ge_u32_e64 s[30:31], v50, v49
	v_cmp_lt_u32_e64 s[34:35], v50, v57
	s_waitcnt lgkmcnt(1)
	v_fmamk_f32 v50, v90, 0x3e000000, v86
	s_waitcnt lgkmcnt(0)
	v_fmamk_f32 v86, v91, 0x3e000000, v88
	s_and_b64 s[0:1], s[4:5], s[8:9]
	v_cndmask_b32_e64 v114, v84, v86, s[0:1]
	v_add_u32_e32 v86, s46, v78
	v_max_i32_e32 v86, -15, v86
	v_add_u32_e32 v86, 15, v86
	v_min_u32_e32 v86, 30, v86
	v_lshl_add_u32 v115, v86, 2, v110
	v_add_u32_e32 v86, s46, v79
	v_max_i32_e32 v86, -15, v86
	v_add_u32_e32 v86, 15, v86
	v_min_u32_e32 v86, 30, v86
	ds_read2_b32 v[90:91], v115 offset1:31
	v_lshl_add_u32 v116, v86, 2, v110
	ds_read2_b32 v[106:107], v116 offset1:31
	s_and_b64 s[4:5], s[10:11], s[12:13]
	s_and_b64 s[8:9], s[14:15], s[16:17]
	s_waitcnt lgkmcnt(1)
	v_fmamk_f32 v88, v92, 0x3e000000, v90
	v_cndmask_b32_e64 v117, v84, v88, s[4:5]
	s_waitcnt lgkmcnt(0)
; #define LAS __attribute__((address_space(3)))
; __device__ __forceinline__ void na_phase(const Frame& F, const bf16* QH, const bf16* VB, const float* rpb, bf16* U) {
;     ...
;             for (int k8 = 0; k8 < 8; ++k8) { const int kc = c0 + 8 * q4 + 4 * (k8 >> 2) + (k8 & 3); okk[k8] = (kc >= cs) && (kc < cs + 16); cofs[k8] = min(max(kc - qcol + 15, 0), 30); }
; #pragma unroll
;             for (int i = 0; i < 8; ++i) { const LAS float* rprow = RP + (h * 15 + (rs + i - r + 7)) * 31;
; #pragma unroll
;                 for (int k8 = 0; k8 < 8; ++k8) { const int blk = 2 * i + (k8 >> 2), e = k8 & 3;
;                     const float bia = rprow[cofs[k8]];
;                     const float sb = acc[blk][e] * 0.125f + bia; const float s = okk[k8] ? sb : -3.0e38f;
;                     acc[blk][e] = s; mx = fmaxf(mx, s); } }
;             mx = fmaxf(mx, __shfl_xor(mx, 16)); mx = fmaxf(mx, __shfl_xor(mx, 32));
	v_fmamk_f32 v88, v93, 0x3e000000, v106
	v_cndmask_b32_e64 v106, v84, v88, s[8:9]
	v_add_u32_e32 v88, s46, v80
	v_max_i32_e32 v88, -15, v88
	v_add_u32_e32 v88, 15, v88
	v_min_u32_e32 v88, 30, v88
	v_lshl_add_u32 v118, v88, 2, v110
	v_add_u32_e32 v88, s46, v81
	v_max_i32_e32 v88, -15, v88
	v_add_u32_e32 v88, 15, v88
	v_min_u32_e32 v88, 30, v88
	ds_read2_b32 v[92:93], v118 offset1:31
	v_lshl_add_u32 v119, v88, 2, v110
	ds_read2_b32 v[108:109], v119 offset1:31
	s_and_b64 s[10:11], s[18:19], s[20:21]
	s_and_b64 s[12:13], s[22:23], s[24:25]
	s_waitcnt lgkmcnt(1)
	v_fmamk_f32 v88, v94, 0x3e000000, v92
	v_cndmask_b32_e64 v120, v84, v88, s[10:11]
	s_waitcnt lgkmcnt(0)
	v_fmamk_f32 v88, v95, 0x3e000000, v108
	v_cndmask_b32_e64 v108, v84, v88, s[12:13]
	v_add_u32_e32 v88, s46, v82
	v_max_i32_e32 v88, -15, v88
	v_add_u32_e32 v88, 15, v88
	v_min_u32_e32 v88, 30, v88
	v_lshl_add_u32 v121, v88, 2, v110
	v_add_u32_e32 v88, s46, v83
	v_max_i32_e32 v88, -15, v88
	v_add_u32_e32 v88, 15, v88
	v_min_u32_e32 v88, 30, v88
	ds_read2_b32 v[94:95], v121 offset1:31
	v_lshl_add_u32 v122, v88, 2, v110
	ds_read2_b32 v[110:111], v122 offset1:31
	v_cndmask_b32_e32 v50, v84, v50, vcc
	v_max3_f32 v86, v50, s77, v114
	s_waitcnt lgkmcnt(1)
	v_fmamk_f32 v88, v96, 0x3e000000, v94
	s_and_b64 s[14:15], s[26:27], s[28:29]
	v_max3_f32 v86, v86, v117, v106
	v_cndmask_b32_e64 v96, v84, v88, s[14:15]
	s_waitcnt lgkmcnt(0)
	v_fmamk_f32 v88, v97, 0x3e000000, v110
	s_and_b64 s[16:17], s[30:31], s[34:35]
	v_max3_f32 v86, v86, v120, v108
	v_cndmask_b32_e64 v97, v84, v88, s[16:17]
	v_fmac_f32_e32 v87, 0x3e000000, v102
	v_fmac_f32_e32 v89, 0x3e000000, v103
	v_max3_f32 v86, v86, v96, v97
	v_cndmask_b32_e32 v102, v84, v87, vcc
	v_cndmask_b32_e64 v103, v84, v89, s[0:1]
	v_fmac_f32_e32 v91, 0x3e000000, v104
	v_fmac_f32_e32 v107, 0x3e000000, v105
	v_max3_f32 v86, v86, v102, v103
	v_cndmask_b32_e64 v104, v84, v91, s[4:5]
	v_cndmask_b32_e64 v105, v84, v107, s[8:9]
	v_fmac_f32_e32 v93, 0x3e000000, v98
	v_fmac_f32_e32 v109, 0x3e000000, v99
	v_max3_f32 v86, v86, v104, v105
	v_cndmask_b32_e64 v98, v84, v93, s[10:11]
	v_cndmask_b32_e64 v99, v84, v109, s[12:13]
	v_max3_f32 v90, v86, v98, v99
	ds_read2_b32 v[86:87], v112 offset0:62 offset1:93
	ds_read2_b32 v[88:89], v113 offset0:62 offset1:93
	v_fmac_f32_e32 v95, 0x3e000000, v100
	v_fmac_f32_e32 v111, 0x3e000000, v101
	v_cndmask_b32_e64 v100, v84, v95, s[14:15]
	v_cndmask_b32_e64 v101, v84, v111, s[16:17]
	s_waitcnt lgkmcnt(1)
	v_fmamk_f32 v44, v44, 0x3e000000, v86
	v_max3_f32 v92, v90, v100, v101
	v_cndmask_b32_e32 v86, v84, v44, vcc
	ds_read2_b32 v[90:91], v115 offset0:62 offset1:93
	s_waitcnt lgkmcnt(1)
	v_fmamk_f32 v44, v45, 0x3e000000, v88
	v_cndmask_b32_e64 v88, v84, v44, s[0:1]
	ds_read2_b32 v[44:45], v116 offset0:62 offset1:93
	v_max3_f32 v94, v92, v86, v88
	s_waitcnt lgkmcnt(1)
	v_fmamk_f32 v46, v46, 0x3e000000, v90
	ds_read2_b32 v[92:93], v118 offset0:62 offset1:93
	v_cndmask_b32_e64 v90, v84, v46, s[4:5]
	s_waitcnt lgkmcnt(1)
	v_fmamk_f32 v44, v47, 0x3e000000, v44
	ds_read2_b32 v[46:47], v119 offset0:62 offset1:93
	v_cndmask_b32_e64 v44, v84, v44, s[8:9]
	s_waitcnt lgkmcnt(1)
	v_fmamk_f32 v40, v40, 0x3e000000, v92
	v_max3_f32 v107, v94, v90, v44
	v_cndmask_b32_e64 v92, v84, v40, s[10:11]
	ds_read2_b32 v[94:95], v121 offset0:62 offset1:93
	s_waitcnt lgkmcnt(1)
	v_fmamk_f32 v46, v41, 0x3e000000, v46
	ds_read2_b32 v[40:41], v122 offset0:62 offset1:93
	v_cndmask_b32_e64 v46, v84, v46, s[12:13]
	v_fmac_f32_e32 v93, 0x3e000000, v32
	s_waitcnt lgkmcnt(1)
	v_fmamk_f32 v42, v42, 0x3e000000, v94
	v_fmac_f32_e32 v47, 0x3e000000, v33
	s_waitcnt lgkmcnt(0)
	v_fmamk_f32 v40, v43, 0x3e000000, v40
	ds_read2_b32 v[32:33], v112 offset0:124 offset1:155
	v_max3_f32 v107, v107, v92, v46
	v_cndmask_b32_e64 v42, v84, v42, s[14:15]
	v_cndmask_b32_e64 v43, v84, v40, s[16:17]
	v_fmac_f32_e32 v87, 0x3e000000, v36
	v_fmac_f32_e32 v89, 0x3e000000, v37
	v_fmac_f32_e32 v95, 0x3e000000, v34
	v_fmac_f32_e32 v41, 0x3e000000, v35
	ds_read2_b32 v[34:35], v113 offset0:124 offset1:155
	v_max3_f32 v40, v107, v42, v43
	v_cndmask_b32_e32 v87, v84, v87, vcc
	v_cndmask_b32_e64 v89, v84, v89, s[0:1]
	v_fmac_f32_e32 v91, 0x3e000000, v38
	v_fmac_f32_e32 v45, 0x3e000000, v39
	v_max3_f32 v36, v40, v87, v89
	v_cndmask_b32_e64 v91, v84, v91, s[4:5]
	v_cndmask_b32_e64 v45, v84, v45, s[8:9]
	v_max3_f32 v36, v36, v91, v45
	v_cndmask_b32_e64 v93, v84, v93, s[10:11]
	v_cndmask_b32_e64 v47, v84, v47, s[12:13]
	v_max3_f32 v36, v36, v93, v47
	v_cndmask_b32_e64 v94, v84, v95, s[14:15]
	v_cndmask_b32_e64 v95, v84, v41, s[16:17]
	s_waitcnt lgkmcnt(1)
	v_fmamk_f32 v20, v20, 0x3e000000, v32
	v_max3_f32 v38, v36, v94, v95
	v_cndmask_b32_e32 v107, v84, v20, vcc
	ds_read2_b32 v[36:37], v115 offset0:124 offset1:155
	s_waitcnt lgkmcnt(1)
	v_fmamk_f32 v20, v21, 0x3e000000, v34
	v_cndmask_b32_e64 v34, v84, v20, s[0:1]
	ds_read2_b32 v[20:21], v116 offset0:124 offset1:155
	v_max3_f32 v32, v38, v107, v34
	s_waitcnt lgkmcnt(1)
	v_fmamk_f32 v22, v22, 0x3e000000, v36
	ds_read2_b32 v[38:39], v118 offset0:124 offset1:155
	v_cndmask_b32_e64 v36, v84, v22, s[4:5]
	s_waitcnt lgkmcnt(1)
	v_fmamk_f32 v20, v23, 0x3e000000, v20
	ds_read2_b32 v[22:23], v119 offset0:124 offset1:155
	ds_read2_b32 v[40:41], v121 offset0:124 offset1:155
	s_waitcnt lgkmcnt(2)
	v_fmamk_f32 v24, v24, 0x3e000000, v38
	v_cndmask_b32_e64 v38, v84, v24, s[10:11]
	v_cndmask_b32_e64 v109, v84, v20, s[8:9]
	s_waitcnt lgkmcnt(1)
	v_fmamk_f32 v22, v25, 0x3e000000, v22
	ds_read2_b32 v[24:25], v122 offset0:124 offset1:155
	v_cndmask_b32_e64 v110, v84, v22, s[12:13]
	s_waitcnt lgkmcnt(1)
	v_fmamk_f32 v22, v26, 0x3e000000, v40
	v_max3_f32 v20, v32, v36, v109
	v_cndmask_b32_e64 v40, v84, v22, s[14:15]
	s_waitcnt lgkmcnt(0)
; #define LAS __attribute__((address_space(3)))
; __device__ __forceinline__ void na_phase(const Frame& F, const bf16* QH, const bf16* VB, const float* rpb, bf16* U) {
;     ...
;             for (int i = 0; i < 8; ++i) { const LAS float* rprow = RP + (h * 15 + (rs + i - r + 7)) * 31;
; #pragma unroll
;                 for (int k8 = 0; k8 < 8; ++k8) { const int blk = 2 * i + (k8 >> 2), e = k8 & 3;
;                     const float bia = rprow[cofs[k8]];
;                     const float sb = acc[blk][e] * 0.125f + bia; const float s = okk[k8] ? sb : -3.0e38f;
;                     acc[blk][e] = s; mx = fmaxf(mx, s); } }
;             mx = fmaxf(mx, __shfl_xor(mx, 16)); mx = fmaxf(mx, __shfl_xor(mx, 32));
;             float sum = 0.f;
; #pragma unroll
;             for (int blk = 0; blk < 16; ++blk)
; #pragma unroll
;                 for (int e = 0; e < 4; ++e) { const float p = __builtin_amdgcn_exp2f((acc[blk][e] - mx) * 1.44269504089f); acc[blk][e] = p; sum += p; }
	v_fmamk_f32 v22, v27, 0x3e000000, v24
	v_max3_f32 v20, v20, v38, v110
	v_cndmask_b32_e64 v111, v84, v22, s[16:17]
	v_fmac_f32_e32 v33, 0x3e000000, v28
	v_fmac_f32_e32 v35, 0x3e000000, v29
	v_max3_f32 v20, v20, v40, v111
	v_cndmask_b32_e32 v123, v84, v33, vcc
	v_cndmask_b32_e64 v35, v84, v35, s[0:1]
	v_fmac_f32_e32 v37, 0x3e000000, v30
	v_fmac_f32_e32 v21, 0x3e000000, v31
	v_max3_f32 v20, v20, v123, v35
	v_cndmask_b32_e64 v37, v84, v37, s[4:5]
	v_cndmask_b32_e64 v124, v84, v21, s[8:9]
	v_fmac_f32_e32 v39, 0x3e000000, v16
	v_fmac_f32_e32 v23, 0x3e000000, v17
	v_max3_f32 v20, v20, v37, v124
	v_cndmask_b32_e64 v125, v84, v39, s[10:11]
	v_cndmask_b32_e64 v126, v84, v23, s[12:13]
	v_max3_f32 v16, v20, v125, v126
	ds_read2_b32 v[20:21], v112 offset0:186 offset1:217
	v_fmac_f32_e32 v41, 0x3e000000, v18
	v_fmac_f32_e32 v25, 0x3e000000, v19
	ds_read2_b32 v[18:19], v113 offset0:186 offset1:217
	v_cndmask_b32_e64 v127, v84, v41, s[14:15]
	v_cndmask_b32_e64 v112, v84, v25, s[16:17]
	s_waitcnt lgkmcnt(1)
	v_fmamk_f32 v12, v12, 0x3e000000, v20
	v_max3_f32 v26, v16, v127, v112
	v_cndmask_b32_e32 v16, v84, v12, vcc
	s_waitcnt lgkmcnt(0)
	v_fmamk_f32 v12, v13, 0x3e000000, v18
	ds_read2_b32 v[22:23], v115 offset0:186 offset1:217
	v_cndmask_b32_e64 v17, v84, v12, s[0:1]
	ds_read2_b32 v[24:25], v116 offset0:186 offset1:217
	v_max3_f32 v12, v26, v16, v17
	ds_read2_b32 v[26:27], v118 offset0:186 offset1:217
	ds_read2_b32 v[28:29], v119 offset0:186 offset1:217
	ds_read2_b32 v[30:31], v121 offset0:186 offset1:217
	ds_read2_b32 v[32:33], v122 offset0:186 offset1:217
	s_waitcnt lgkmcnt(5)
	v_fmamk_f32 v13, v14, 0x3e000000, v22
	v_cndmask_b32_e64 v18, v84, v13, s[4:5]
	s_waitcnt lgkmcnt(4)
	v_fmamk_f32 v13, v15, 0x3e000000, v24
	s_waitcnt lgkmcnt(3)
	v_fmamk_f32 v8, v8, 0x3e000000, v26
	v_cndmask_b32_e64 v15, v84, v13, s[8:9]
	v_cndmask_b32_e64 v14, v84, v8, s[10:11]
	s_waitcnt lgkmcnt(2)
	v_fmamk_f32 v8, v9, 0x3e000000, v28
	v_max3_f32 v12, v12, v18, v15
	v_cndmask_b32_e64 v13, v84, v8, s[12:13]
	s_waitcnt lgkmcnt(1)
	v_fmamk_f32 v9, v10, 0x3e000000, v30
	v_max3_f32 v8, v12, v14, v13
	v_cndmask_b32_e64 v12, v84, v9, s[14:15]
	s_waitcnt lgkmcnt(0)
	v_fmamk_f32 v9, v11, 0x3e000000, v32
	v_cndmask_b32_e64 v11, v84, v9, s[16:17]
	v_fmac_f32_e32 v21, 0x3e000000, v4
	v_fmac_f32_e32 v19, 0x3e000000, v5
	v_max3_f32 v8, v8, v12, v11
	v_cndmask_b32_e32 v10, v84, v21, vcc
	v_cndmask_b32_e64 v9, v84, v19, s[0:1]
	v_fmac_f32_e32 v23, 0x3e000000, v6
	v_fmac_f32_e32 v25, 0x3e000000, v7
	v_max3_f32 v4, v8, v10, v9
	v_cndmask_b32_e64 v8, v84, v23, s[4:5]
	v_cndmask_b32_e64 v6, v84, v25, s[8:9]
	v_fmac_f32_e32 v27, 0x3e000000, v0
	v_fmac_f32_e32 v29, 0x3e000000, v1
	v_max3_f32 v7, v4, v8, v6
	v_cndmask_b32_e64 v5, v84, v27, s[10:11]
	v_cndmask_b32_e64 v4, v84, v29, s[12:13]
	v_fmac_f32_e32 v31, 0x3e000000, v2
	v_fmac_f32_e32 v33, 0x3e000000, v3
	v_max3_f32 v7, v7, v5, v4
	v_cndmask_b32_e64 v1, v84, v31, s[14:15]
	v_cndmask_b32_e64 v0, v84, v33, s[16:17]
	v_max3_f32 v2, v7, v1, v0
	ds_bpermute_b32 v3, v73, v2
	s_lshr_b32 s0, s46, 3
	s_cmpk_eq_i32 s87, 0x7440
	s_waitcnt lgkmcnt(0)
	v_max_f32_e32 v3, v3, v3
	v_max_f32_e32 v2, v2, v3
	ds_bpermute_b32 v3, v74, v2
	s_waitcnt lgkmcnt(0)
	v_max_f32_e32 v3, v3, v3
	v_max_f32_e32 v2, v2, v3
	v_sub_f32_e32 v20, v117, v2
	v_mul_f32_e32 v20, 0x3fb8aa3b, v20
	v_exp_f32_e32 v115, v20
	v_sub_f32_e32 v20, v106, v2
	v_mul_f32_e32 v20, 0x3fb8aa3b, v20
	v_exp_f32_e32 v118, v20
	v_sub_f32_e32 v20, v120, v2
	v_mul_f32_e32 v20, 0x3fb8aa3b, v20
	v_exp_f32_e32 v128, v20
	v_sub_f32_e32 v20, v108, v2
	v_mul_f32_e32 v20, 0x3fb8aa3b, v20
	v_exp_f32_e32 v129, v20
	v_sub_f32_e32 v20, v96, v2
	v_mul_f32_e32 v20, 0x3fb8aa3b, v20
	v_exp_f32_e32 v130, v20
	v_sub_f32_e32 v20, v97, v2
	v_mul_f32_e32 v20, 0x3fb8aa3b, v20
	v_exp_f32_e32 v131, v20
	v_sub_f32_e32 v20, v102, v2
	v_mul_f32_e32 v20, 0x3fb8aa3b, v20
	v_exp_f32_e32 v142, v20
	v_sub_f32_e32 v20, v103, v2
	v_mul_f32_e32 v20, 0x3fb8aa3b, v20
	v_exp_f32_e32 v143, v20
	v_sub_f32_e32 v20, v104, v2
	v_mul_f32_e32 v20, 0x3fb8aa3b, v20
	v_exp_f32_e32 v144, v20
	v_sub_f32_e32 v20, v105, v2
	v_mul_f32_e32 v20, 0x3fb8aa3b, v20
	v_exp_f32_e32 v145, v20
	v_sub_f32_e32 v20, v98, v2
	v_mul_f32_e32 v20, 0x3fb8aa3b, v20
	v_exp_f32_e32 v146, v20
	v_sub_f32_e32 v20, v99, v2
	v_mul_f32_e32 v20, 0x3fb8aa3b, v20
	v_exp_f32_e32 v147, v20
	v_sub_f32_e32 v20, v100, v2
	v_mul_f32_e32 v20, 0x3fb8aa3b, v20
	v_exp_f32_e32 v148, v20
	v_sub_f32_e32 v20, v101, v2
	v_mul_f32_e32 v20, 0x3fb8aa3b, v20
	v_exp_f32_e32 v149, v20
	v_sub_f32_e32 v20, v86, v2
	v_mul_f32_e32 v20, 0x3fb8aa3b, v20
	v_exp_f32_e32 v152, v20
	v_sub_f32_e32 v20, v88, v2
	v_mul_f32_e32 v20, 0x3fb8aa3b, v20
	v_exp_f32_e32 v153, v20
	v_sub_f32_e32 v20, v90, v2
	v_mul_f32_e32 v20, 0x3fb8aa3b, v20
	v_exp_f32_e32 v154, v20
	v_sub_f32_e32 v20, v44, v2
	v_mul_f32_e32 v20, 0x3fb8aa3b, v20
	v_exp_f32_e32 v155, v20
	v_sub_f32_e32 v20, v92, v2
	v_mul_f32_e32 v20, 0x3fb8aa3b, v20
	v_exp_f32_e32 v156, v20
	v_sub_f32_e32 v20, v46, v2
	v_mul_f32_e32 v20, 0x3fb8aa3b, v20
	v_exp_f32_e32 v157, v20
	v_sub_f32_e32 v20, v42, v2
	v_mul_f32_e32 v20, 0x3fb8aa3b, v20
	v_exp_f32_e32 v158, v20
	v_sub_f32_e32 v20, v43, v2
	v_mul_f32_e32 v20, 0x3fb8aa3b, v20
	v_exp_f32_e32 v159, v20
	v_sub_f32_e32 v20, v87, v2
	v_mul_f32_e32 v20, 0x3fb8aa3b, v20
	v_exp_f32_e32 v160, v20
	v_sub_f32_e32 v20, v89, v2
	v_mul_f32_e32 v20, 0x3fb8aa3b, v20
	v_exp_f32_e32 v161, v20
	v_sub_f32_e32 v20, v91, v2
	v_mul_f32_e32 v20, 0x3fb8aa3b, v20
	v_exp_f32_e32 v162, v20
	v_sub_f32_e32 v20, v45, v2
	v_mul_f32_e32 v20, 0x3fb8aa3b, v20
	v_exp_f32_e32 v163, v20
	v_sub_f32_e32 v20, v93, v2
	v_mul_f32_e32 v20, 0x3fb8aa3b, v20
; __device__ __forceinline__ unsigned pk2(float lo, float hi) { unsigned r; asm("v_cvt_pk_bf16_f32 %0, %1, %2" : "=v"(r) : "v"(lo), "v"(hi)); return r; }
; __device__ __forceinline__ void na_phase(const Frame& F, const bf16* QH, const bf16* VB, const float* rpb, bf16* U) {
;     ...
;             float sum = 0.f;
; #pragma unroll
;             for (int blk = 0; blk < 16; ++blk)
; #pragma unroll
;                 for (int e = 0; e < 4; ++e) { const float p = __builtin_amdgcn_exp2f((acc[blk][e] - mx) * 1.44269504089f); acc[blk][e] = p; sum += p; }
;             sum += __shfl_xor(sum, 16); sum += __shfl_xor(sum, 32);
;             const float inv = 1.0f / sum;
;             f32x4 o[4];
; #pragma unroll
;             for (int db = 0; db < 4; ++db) o[db] = (f32x4){0.f, 0.f, 0.f, 0.f};
; #pragma unroll
;             for (int i = 0; i < 8; ++i) {
;                 v4u pw; pw.x = pk2(acc[2 * i][0], acc[2 * i][1]); pw.y = pk2(acc[2 * i][2], acc[2 * i][3]); pw.z = pk2(acc[2 * i + 1][0], acc[2 * i + 1][1]); pw.w = pk2(acc[2 * i + 1][2], acc[2 * i + 1][3]);
;                 const bf16x8 pf = __builtin_bit_cast(bf16x8, pw);
;                 const size_t vrow = (((size_t)h * 512 + b * 256 + rs + i) * 8 + (c0 >> 3) + q4) * 512;
; #pragma unroll
;                 for (int db = 0; db < 4; ++db) { const bf16x8 vfrag = *(const bf16x8*)(VB + vrow + (16 * db + n) * 8);
;                     o[db] = __builtin_amdgcn_mfma_f32_16x16x32_bf16(vfrag, pf, o[db], 0, 0, 0); }
	v_exp_f32_e32 v164, v20
	v_sub_f32_e32 v20, v47, v2
	v_mul_f32_e32 v20, 0x3fb8aa3b, v20
	v_exp_f32_e32 v165, v20
	v_sub_f32_e32 v20, v94, v2
	v_mul_f32_e32 v20, 0x3fb8aa3b, v20
	v_exp_f32_e32 v166, v20
	v_sub_f32_e32 v20, v95, v2
	v_mul_f32_e32 v20, 0x3fb8aa3b, v20
	v_exp_f32_e32 v167, v20
	v_sub_f32_e32 v20, v107, v2
	v_mul_f32_e32 v20, 0x3fb8aa3b, v20
	v_exp_f32_e32 v168, v20
	v_sub_f32_e32 v20, v34, v2
	v_mul_f32_e32 v20, 0x3fb8aa3b, v20
	v_exp_f32_e32 v169, v20
	v_sub_f32_e32 v20, v36, v2
	v_sub_f32_e32 v3, v50, v2
	v_mul_f32_e32 v20, 0x3fb8aa3b, v20
	v_mul_f32_e32 v3, 0x3fb8aa3b, v3
	v_sub_f32_e32 v7, v114, v2
	v_exp_f32_e32 v170, v20
	v_sub_f32_e32 v20, v109, v2
	v_exp_f32_e32 v3, v3
	v_mul_f32_e32 v7, 0x3fb8aa3b, v7
	v_mul_f32_e32 v20, 0x3fb8aa3b, v20
	v_exp_f32_e32 v7, v7
	v_exp_f32_e32 v171, v20
	v_sub_f32_e32 v20, v38, v2
	v_mul_f32_e32 v20, 0x3fb8aa3b, v20
	v_exp_f32_e32 v172, v20
	v_sub_f32_e32 v20, v110, v2
	v_add_f32_e32 v19, 0, v3
	v_mul_f32_e32 v20, 0x3fb8aa3b, v20
	v_add_f32_e32 v19, v7, v19
	v_exp_f32_e32 v173, v20
	v_sub_f32_e32 v20, v40, v2
	v_add_f32_e32 v19, v115, v19
	v_mul_f32_e32 v20, 0x3fb8aa3b, v20
	v_add_f32_e32 v19, v118, v19
	v_exp_f32_e32 v174, v20
	v_sub_f32_e32 v20, v111, v2
	v_add_f32_e32 v19, v128, v19
	v_mul_f32_e32 v20, 0x3fb8aa3b, v20
	v_add_f32_e32 v19, v129, v19
	v_exp_f32_e32 v175, v20
	v_sub_f32_e32 v20, v123, v2
	v_add_lshl_u32 v50, s0, v72, 10
	v_add_f32_e32 v19, v130, v19
	v_mul_f32_e32 v24, 0x3fb8aa3b, v20
	v_lshl_add_u64 v[20:21], v[60:61], 0, v[50:51]
	v_sub_f32_e32 v28, v35, v2
	v_add_f32_e32 v19, v131, v19
	v_lshl_add_u64 v[150:151], s[70:71], 0, v[20:21]
	v_mul_f32_e32 v34, 0x3fb8aa3b, v28
	v_add_f32_e32 v19, v142, v19
	v_add_co_u32_e32 v32, vcc, s78, v150
	v_exp_f32_e32 v176, v34
	v_sub_f32_e32 v34, v37, v2
	v_add_f32_e32 v19, v143, v19
	v_addc_co_u32_e32 v33, vcc, 0, v151, vcc
	v_mul_f32_e32 v34, 0x3fb8aa3b, v34
	v_add_f32_e32 v19, v144, v19
	s_mov_b64 exec, s[92:93]
	global_load_dwordx4 v[20:23], v[32:33], off
	s_mov_b64 exec, s[98:99]
	v_mov_b32_e32 v20, 0
	v_mov_b32_e32 v21, 0
	v_mov_b32_e32 v22, 0
	v_mov_b32_e32 v23, 0
	s_mov_b64 exec, -1
	v_exp_f32_e32 v50, v24
	s_mov_b64 exec, s[92:93]
	global_load_dwordx4 v[24:27], v[32:33], off offset:256
	s_mov_b64 exec, s[98:99]
	v_mov_b32_e32 v24, 0
	v_mov_b32_e32 v25, 0
	v_mov_b32_e32 v26, 0
	v_mov_b32_e32 v27, 0
	s_mov_b64 exec, -1
	v_exp_f32_e32 v177, v34
	v_sub_f32_e32 v34, v124, v2
	v_add_co_u32_e32 v86, vcc, s79, v150
	v_add_f32_e32 v19, v145, v19
	v_mul_f32_e32 v36, 0x3fb8aa3b, v34
	v_addc_co_u32_e32 v87, vcc, 0, v151, vcc
	v_add_f32_e32 v19, v146, v19
	s_mov_b64 exec, s[92:93]
	global_load_dwordx4 v[28:31], v[32:33], off offset:512
	s_mov_b64 exec, s[98:99]
	v_mov_b32_e32 v28, 0
	v_mov_b32_e32 v29, 0
	v_mov_b32_e32 v30, 0
	v_mov_b32_e32 v31, 0
	s_mov_b64 exec, -1
	v_exp_f32_e32 v178, v36
	s_mov_b64 exec, s[92:93]
	global_load_dwordx4 v[36:39], v[86:87], off
	s_mov_b64 exec, s[98:99]
	v_mov_b32_e32 v36, 0
	v_mov_b32_e32 v37, 0
	v_mov_b32_e32 v38, 0
	v_mov_b32_e32 v39, 0
	s_mov_b64 exec, -1
	v_sub_f32_e32 v44, v125, v2
	s_mov_b64 exec, s[92:93]
	global_load_dwordx4 v[32:35], v[32:33], off offset:768
	s_mov_b64 exec, s[98:99]
	v_mov_b32_e32 v32, 0
	v_mov_b32_e32 v33, 0
	v_mov_b32_e32 v34, 0
	v_mov_b32_e32 v35, 0
	s_mov_b64 exec, -1
	v_add_f32_e32 v19, v147, v19
	v_mul_f32_e32 v44, 0x3fb8aa3b, v44
	v_add_f32_e32 v19, v148, v19
	s_mov_b64 exec, s[92:93]
	global_load_dwordx4 v[40:43], v[86:87], off offset:256
	s_mov_b64 exec, s[98:99]
	v_mov_b32_e32 v40, 0
	v_mov_b32_e32 v41, 0
	v_mov_b32_e32 v42, 0
	v_mov_b32_e32 v43, 0
	s_mov_b64 exec, -1
	v_exp_f32_e32 v179, v44
	v_sub_f32_e32 v44, v126, v2
	v_sub_f32_e32 v88, v127, v2
	v_add_co_u32_e32 v102, vcc, s80, v150
	v_add_f32_e32 v19, v149, v19
	v_mul_f32_e32 v44, 0x3fb8aa3b, v44
	v_mul_f32_e32 v88, 0x3fb8aa3b, v88
	v_addc_co_u32_e32 v103, vcc, 0, v151, vcc
	v_add_f32_e32 v19, v152, v19
	v_exp_f32_e32 v180, v44
	s_mov_b64 exec, s[92:93]
	global_load_dwordx4 v[44:47], v[86:87], off offset:512
	s_mov_b64 exec, s[98:99]
	v_mov_b32_e32 v44, 0
	v_mov_b32_e32 v45, 0
	v_mov_b32_e32 v46, 0
	v_mov_b32_e32 v47, 0
	s_mov_b64 exec, -1
	s_mov_b64 exec, s[92:93]
	global_load_dwordx4 v[90:93], v[102:103], off
	s_mov_b64 exec, s[98:99]
	v_mov_b32_e32 v90, 0
	v_mov_b32_e32 v91, 0
	v_mov_b32_e32 v92, 0
	v_mov_b32_e32 v93, 0
	s_mov_b64 exec, -1
	v_exp_f32_e32 v181, v88
	s_mov_b64 exec, s[92:93]
	global_load_dwordx4 v[86:89], v[86:87], off offset:768
	s_mov_b64 exec, s[98:99]
	v_mov_b32_e32 v86, 0
	v_mov_b32_e32 v87, 0
	v_mov_b32_e32 v88, 0
	v_mov_b32_e32 v89, 0
	s_mov_b64 exec, -1
	v_add_f32_e32 v19, v153, v19
	v_add_f32_e32 v19, v154, v19
	v_add_f32_e32 v19, v155, v19
	v_add_f32_e32 v19, v156, v19
	v_add_f32_e32 v19, v157, v19
	v_add_f32_e32 v19, v158, v19
	v_add_f32_e32 v19, v159, v19
	v_add_f32_e32 v19, v160, v19
	v_add_f32_e32 v19, v161, v19
	v_add_f32_e32 v19, v162, v19
	v_add_f32_e32 v19, v163, v19
	v_add_f32_e32 v19, v164, v19
	v_add_f32_e32 v19, v165, v19
	v_add_f32_e32 v19, v166, v19
	v_add_f32_e32 v19, v167, v19
	v_add_f32_e32 v19, v168, v19
	v_add_f32_e32 v19, v169, v19
	v_add_f32_e32 v19, v170, v19
	v_add_f32_e32 v19, v171, v19
	v_add_f32_e32 v19, v172, v19
	v_add_f32_e32 v19, v173, v19
	s_mov_b64 exec, s[92:93]
	global_load_dwordx4 v[98:101], v[102:103], off offset:512
	s_mov_b64 exec, s[98:99]
	v_mov_b32_e32 v98, 0
	v_mov_b32_e32 v99, 0
	v_mov_b32_e32 v100, 0
	v_mov_b32_e32 v101, 0
	s_mov_b64 exec, -1
	v_add_f32_e32 v19, v174, v19
	v_add_f32_e32 v19, v175, v19
	v_add_f32_e32 v19, v50, v19
	v_add_f32_e32 v19, v176, v19
	v_sub_f32_e32 v94, v112, v2
	v_add_f32_e32 v19, v177, v19
	v_mul_f32_e32 v94, 0x3fb8aa3b, v94
; __device__ __forceinline__ unsigned pk2(float lo, float hi) { unsigned r; asm("v_cvt_pk_bf16_f32 %0, %1, %2" : "=v"(r) : "v"(lo), "v"(hi)); return r; }
; __device__ __forceinline__ void na_phase(const Frame& F, const bf16* QH, const bf16* VB, const float* rpb, bf16* U) {
;     ...
; #pragma unroll
;             for (int i = 0; i < 8; ++i) {
;                 v4u pw; pw.x = pk2(acc[2 * i][0], acc[2 * i][1]); pw.y = pk2(acc[2 * i][2], acc[2 * i][3]); pw.z = pk2(acc[2 * i + 1][0], acc[2 * i + 1][1]); pw.w = pk2(acc[2 * i + 1][2], acc[2 * i + 1][3]);
;                 const bf16x8 pf = __builtin_bit_cast(bf16x8, pw);
;                 const size_t vrow = (((size_t)h * 512 + b * 256 + rs + i) * 8 + (c0 >> 3) + q4) * 512;
; #pragma unroll
;                 for (int db = 0; db < 4; ++db) { const bf16x8 vfrag = *(const bf16x8*)(VB + vrow + (16 * db + n) * 8);
;                     o[db] = __builtin_amdgcn_mfma_f32_16x16x32_bf16(vfrag, pf, o[db], 0, 0, 0); }
;             }
	v_sub_f32_e32 v16, v16, v2
	v_add_f32_e32 v19, v178, v19
	v_exp_f32_e32 v182, v94
	v_mul_f32_e32 v16, 0x3fb8aa3b, v16
	v_add_f32_e32 v19, v179, v19
	s_mov_b64 exec, s[92:93]
	global_load_dwordx4 v[94:97], v[102:103], off offset:256
	s_mov_b64 exec, s[98:99]
	v_mov_b32_e32 v94, 0
	v_mov_b32_e32 v95, 0
	v_mov_b32_e32 v96, 0
	v_mov_b32_e32 v97, 0
	s_mov_b64 exec, -1
	v_exp_f32_e32 v183, v16
	v_add_f32_e32 v19, v180, v19
	v_add_f32_e32 v19, v181, v19
	v_sub_f32_e32 v16, v17, v2
	v_sub_f32_e32 v107, v18, v2
	v_add_co_u32_e32 v116, vcc, s81, v150
	v_add_f32_e32 v106, v182, v19
	v_mul_f32_e32 v16, 0x3fb8aa3b, v16
	v_addc_co_u32_e32 v117, vcc, 0, v151, vcc
	v_mul_f32_e32 v107, 0x3fb8aa3b, v107
	v_exp_f32_e32 v184, v16
	s_mov_b64 exec, s[92:93]
	global_load_dwordx4 v[16:19], v[116:117], off
	s_mov_b64 exec, s[98:99]
	v_mov_b32_e32 v16, 0
	v_mov_b32_e32 v17, 0
	v_mov_b32_e32 v18, 0
	v_mov_b32_e32 v19, 0
	s_mov_b64 exec, -1
	v_exp_f32_e32 v185, v107
	s_mov_b64 exec, s[92:93]
	global_load_dwordx4 v[102:105], v[102:103], off offset:768
	s_mov_b64 exec, s[98:99]
	v_mov_b32_e32 v102, 0
	v_mov_b32_e32 v103, 0
	v_mov_b32_e32 v104, 0
	v_mov_b32_e32 v105, 0
	s_mov_b64 exec, -1
	v_add_f32_e32 v110, v183, v106
	s_mov_b64 exec, s[92:93]
	global_load_dwordx4 v[106:109], v[116:117], off offset:256
	s_mov_b64 exec, s[98:99]
	v_mov_b32_e32 v106, 0
	v_mov_b32_e32 v107, 0
	v_mov_b32_e32 v108, 0
	v_mov_b32_e32 v109, 0
	s_mov_b64 exec, -1
	v_add_f32_e32 v110, v184, v110
	v_add_f32_e32 v132, v185, v110
	s_mov_b64 exec, s[92:93]
	global_load_dwordx4 v[110:113], v[116:117], off offset:512
	s_mov_b64 exec, s[98:99]
	v_mov_b32_e32 v110, 0
	v_mov_b32_e32 v111, 0
	v_mov_b32_e32 v112, 0
	v_mov_b32_e32 v113, 0
	s_mov_b64 exec, -1
	v_cvt_pk_bf16_f32 v114, v3, v7
	v_cvt_pk_bf16_f32 v115, v115, v118
	s_mov_b64 exec, s[92:93]
	global_load_dwordx4 v[118:121], v[116:117], off offset:768
	s_mov_b64 exec, s[98:99]
	v_mov_b32_e32 v118, 0
	v_mov_b32_e32 v119, 0
	v_mov_b32_e32 v120, 0
	v_mov_b32_e32 v121, 0
	s_mov_b64 exec, -1
	v_add_co_u32_e32 v134, vcc, s82, v150
	v_cvt_pk_bf16_f32 v116, v128, v129
	v_cvt_pk_bf16_f32 v117, v130, v131
	v_sub_f32_e32 v15, v15, v2
	s_waitcnt vmcnt(15)
	v_mfma_f32_16x16x32_bf16 v[20:23], v[20:23], v[114:117], 0
	v_addc_co_u32_e32 v135, vcc, 0, v151, vcc
	v_mul_f32_e32 v15, 0x3fb8aa3b, v15
	s_waitcnt vmcnt(14)
	v_mfma_f32_16x16x32_bf16 v[24:27], v[24:27], v[114:117], 0
	v_sub_f32_e32 v7, v14, v2
	v_add_co_u32_e32 v14, vcc, s83, v150
	s_waitcnt vmcnt(11)
	v_mfma_f32_16x16x32_bf16 v[32:35], v[32:35], v[114:117], 0
	v_exp_f32_e32 v186, v15
	v_addc_co_u32_e32 v15, vcc, 0, v151, vcc
	v_mfma_f32_16x16x32_bf16 v[28:31], v[28:31], v[114:117], 0
	s_mov_b64 exec, s[92:93]
	global_load_dwordx4 v[138:141], v[14:15], off
	s_mov_b64 exec, s[98:99]
	v_mov_b32_e32 v138, 0
	v_mov_b32_e32 v139, 0
	v_mov_b32_e32 v140, 0
	v_mov_b32_e32 v141, 0
	s_mov_b64 exec, -1
	v_cvt_pk_bf16_f32 v114, v142, v143
	v_cvt_pk_bf16_f32 v115, v144, v145
	s_mov_b64 exec, s[92:93]
	global_load_dwordx4 v[142:145], v[14:15], off offset:256
	s_mov_b64 exec, s[98:99]
	v_mov_b32_e32 v142, 0
	v_mov_b32_e32 v143, 0
	v_mov_b32_e32 v144, 0
	v_mov_b32_e32 v145, 0
	s_mov_b64 exec, -1
	v_cvt_pk_bf16_f32 v116, v146, v147
	v_cvt_pk_bf16_f32 v117, v148, v149
	s_mov_b64 exec, s[92:93]
	global_load_dwordx4 v[122:125], v[134:135], off
	s_mov_b64 exec, s[98:99]
	v_mov_b32_e32 v122, 0
	v_mov_b32_e32 v123, 0
	v_mov_b32_e32 v124, 0
	v_mov_b32_e32 v125, 0
	s_mov_b64 exec, -1
	s_mov_b64 exec, s[92:93]
	global_load_dwordx4 v[126:129], v[134:135], off offset:256
	s_mov_b64 exec, s[98:99]
	v_mov_b32_e32 v126, 0
	v_mov_b32_e32 v127, 0
	v_mov_b32_e32 v128, 0
	v_mov_b32_e32 v129, 0
	s_mov_b64 exec, -1
	s_nop 1
	v_mfma_f32_16x16x32_bf16 v[20:23], v[36:39], v[114:117], v[20:23]
	s_mov_b64 exec, s[92:93]
	global_load_dwordx4 v[36:39], v[14:15], off offset:512
	s_mov_b64 exec, s[98:99]
	v_mov_b32_e32 v36, 0
	v_mov_b32_e32 v37, 0
	v_mov_b32_e32 v38, 0
	v_mov_b32_e32 v39, 0
	s_mov_b64 exec, -1
	v_add_f32_e32 v3, v186, v132
	s_mov_b64 exec, s[92:93]
	global_load_dwordx4 v[130:133], v[134:135], off offset:512
	s_mov_b64 exec, s[98:99]
	v_mov_b32_e32 v130, 0
	v_mov_b32_e32 v131, 0
	v_mov_b32_e32 v132, 0
	v_mov_b32_e32 v133, 0
	s_mov_b64 exec, -1
	s_waitcnt vmcnt(16)
	v_mfma_f32_16x16x32_bf16 v[24:27], v[40:43], v[114:117], v[24:27]
	s_mov_b64 exec, s[92:93]
	global_load_dwordx4 v[40:43], v[14:15], off offset:768
	s_mov_b64 exec, s[98:99]
	v_mov_b32_e32 v40, 0
	v_mov_b32_e32 v41, 0
	v_mov_b32_e32 v42, 0
	v_mov_b32_e32 v43, 0
	s_mov_b64 exec, -1
	v_add_co_u32_e32 v14, vcc, s84, v150
	s_waitcnt vmcnt(14)
	v_mfma_f32_16x16x32_bf16 v[32:35], v[86:89], v[114:117], v[32:35]
	v_addc_co_u32_e32 v15, vcc, 0, v151, vcc
	v_cvt_pk_bf16_f32 v87, v154, v155
	v_add_co_u32_e32 v154, vcc, s85, v150
	v_cvt_pk_bf16_f32 v86, v152, v153
	s_mov_b64 exec, s[92:93]
	global_load_dwordx4 v[146:149], v[14:15], off
	s_mov_b64 exec, s[98:99]
	v_mov_b32_e32 v146, 0
	v_mov_b32_e32 v147, 0
	v_mov_b32_e32 v148, 0
	v_mov_b32_e32 v149, 0
	s_mov_b64 exec, -1
	s_nop 0
	v_addc_co_u32_e32 v155, vcc, 0, v151, vcc
	s_mov_b64 exec, s[92:93]
	global_load_dwordx4 v[150:153], v[154:155], off
	s_mov_b64 exec, s[98:99]
	v_mov_b32_e32 v150, 0
	v_mov_b32_e32 v151, 0
	v_mov_b32_e32 v152, 0
	v_mov_b32_e32 v153, 0
	s_mov_b64 exec, -1
	s_nop 1
	v_mfma_f32_16x16x32_bf16 v[28:31], v[44:47], v[114:117], v[28:31]
	s_mov_b64 exec, s[92:93]
	global_load_dwordx4 v[134:137], v[134:135], off offset:768
	s_mov_b64 exec, s[98:99]
	v_mov_b32_e32 v134, 0
	v_mov_b32_e32 v135, 0
	v_mov_b32_e32 v136, 0
	v_mov_b32_e32 v137, 0
	s_mov_b64 exec, -1
	v_cvt_pk_bf16_f32 v88, v156, v157
	s_mov_b64 exec, s[92:93]
	global_load_dwordx4 v[44:47], v[14:15], off offset:256
	s_mov_b64 exec, s[98:99]
	v_mov_b32_e32 v44, 0
	v_mov_b32_e32 v45, 0
	v_mov_b32_e32 v46, 0
	v_mov_b32_e32 v47, 0
	s_mov_b64 exec, -1
	s_mov_b64 exec, s[92:93]
	global_load_dwordx4 v[114:117], v[14:15], off offset:512
	s_mov_b64 exec, s[98:99]
	v_mov_b32_e32 v114, 0
	v_mov_b32_e32 v115, 0
	v_mov_b32_e32 v116, 0
	v_mov_b32_e32 v117, 0
	s_mov_b64 exec, -1
	v_cvt_pk_bf16_f32 v89, v158, v159
	v_mul_f32_e32 v7, 0x3fb8aa3b, v7
	v_mfma_f32_16x16x32_bf16 v[20:23], v[90:93], v[86:89], v[20:23]
	s_mov_b64 exec, s[92:93]
	global_load_dwordx4 v[90:93], v[14:15], off offset:768
	s_mov_b64 exec, s[98:99]
	v_mov_b32_e32 v90, 0
	v_mov_b32_e32 v91, 0
	v_mov_b32_e32 v92, 0
	v_mov_b32_e32 v93, 0
	s_mov_b64 exec, -1
	v_exp_f32_e32 v187, v7
	v_sub_f32_e32 v7, v13, v2
	v_mul_f32_e32 v7, 0x3fb8aa3b, v7
	v_exp_f32_e32 v188, v7
	v_sub_f32_e32 v7, v12, v2
	s_waitcnt vmcnt(19)
; __device__ __forceinline__ unsigned pk2(float lo, float hi) { unsigned r; asm("v_cvt_pk_bf16_f32 %0, %1, %2" : "=v"(r) : "v"(lo), "v"(hi)); return r; }
; __device__ __forceinline__ void na_phase(const Frame& F, const bf16* QH, const bf16* VB, const float* rpb, bf16* U) {
;     ...
; #pragma unroll
;             for (int i = 0; i < 8; ++i) {
;                 v4u pw; pw.x = pk2(acc[2 * i][0], acc[2 * i][1]); pw.y = pk2(acc[2 * i][2], acc[2 * i][3]); pw.z = pk2(acc[2 * i + 1][0], acc[2 * i + 1][1]); pw.w = pk2(acc[2 * i + 1][2], acc[2 * i + 1][3]);
;                 const bf16x8 pf = __builtin_bit_cast(bf16x8, pw);
;                 const size_t vrow = (((size_t)h * 512 + b * 256 + rs + i) * 8 + (c0 >> 3) + q4) * 512;
; #pragma unroll
;                 for (int db = 0; db < 4; ++db) { const bf16x8 vfrag = *(const bf16x8*)(VB + vrow + (16 * db + n) * 8);
;                     o[db] = __builtin_amdgcn_mfma_f32_16x16x32_bf16(vfrag, pf, o[db], 0, 0, 0); }
;             }
; #pragma unroll
;             for (int db = 0; db < 4; ++db) { v2u w; w.x = pk2(o[db][0] * inv, o[db][1] * inv); w.y = pk2(o[db][2] * inv, o[db][3] * inv);
;                 *(v2u*)(U + tokq * DM + h * 64 + 16 * db + 4 * q4) = w; }
;         }
	v_mfma_f32_16x16x32_bf16 v[12:15], v[98:101], v[86:89], v[28:31]
	v_mul_f32_e32 v7, 0x3fb8aa3b, v7
	v_exp_f32_e32 v156, v7
	v_sub_f32_e32 v7, v11, v2
	s_mov_b64 exec, s[92:93]
	global_load_dwordx4 v[28:31], v[154:155], off offset:256
	s_mov_b64 exec, s[98:99]
	v_mov_b32_e32 v28, 0
	v_mov_b32_e32 v29, 0
	v_mov_b32_e32 v30, 0
	v_mov_b32_e32 v31, 0
	s_mov_b64 exec, -1
	s_waitcnt vmcnt(19)
	v_mfma_f32_16x16x32_bf16 v[24:27], v[94:97], v[86:89], v[24:27]
	s_mov_b64 exec, s[92:93]
	global_load_dwordx4 v[94:97], v[154:155], off offset:512
	s_mov_b64 exec, s[98:99]
	v_mov_b32_e32 v94, 0
	v_mov_b32_e32 v95, 0
	v_mov_b32_e32 v96, 0
	v_mov_b32_e32 v97, 0
	s_mov_b64 exec, -1
	v_mul_f32_e32 v7, 0x3fb8aa3b, v7
	v_exp_f32_e32 v98, v7
	s_waitcnt vmcnt(18)
	v_mfma_f32_16x16x32_bf16 v[32:35], v[102:105], v[86:89], v[32:35]
	v_cvt_pk_bf16_f32 v86, v160, v161
	v_cvt_pk_bf16_f32 v87, v162, v163
	v_cvt_pk_bf16_f32 v88, v164, v165
	v_cvt_pk_bf16_f32 v89, v166, v167
	v_sub_f32_e32 v7, v10, v2
	v_mfma_f32_16x16x32_bf16 v[16:19], v[16:19], v[86:89], v[20:23]
	v_mul_f32_e32 v7, 0x3fb8aa3b, v7
	v_exp_f32_e32 v99, v7
	v_sub_f32_e32 v7, v9, v2
	s_waitcnt vmcnt(17)
	v_mfma_f32_16x16x32_bf16 v[20:23], v[106:109], v[86:89], v[24:27]
	v_mul_f32_e32 v7, 0x3fb8aa3b, v7
	v_add_f32_e32 v3, v187, v3
	v_exp_f32_e32 v100, v7
	s_mov_b64 exec, s[92:93]
	global_load_dwordx4 v[24:27], v[154:155], off offset:768
	s_mov_b64 exec, s[98:99]
	v_mov_b32_e32 v24, 0
	v_mov_b32_e32 v25, 0
	v_mov_b32_e32 v26, 0
	v_mov_b32_e32 v27, 0
	s_mov_b64 exec, -1
	s_waitcnt vmcnt(17)
	v_mfma_f32_16x16x32_bf16 v[10:13], v[110:113], v[86:89], v[12:15]
	v_sub_f32_e32 v7, v8, v2
	v_add_f32_e32 v3, v188, v3
	v_mul_f32_e32 v7, 0x3fb8aa3b, v7
	s_waitcnt vmcnt(16)
	v_mfma_f32_16x16x32_bf16 v[32:35], v[118:121], v[86:89], v[32:35]
	v_sub_f32_e32 v6, v6, v2
	v_add_f32_e32 v3, v156, v3
	v_exp_f32_e32 v101, v7
	v_mul_f32_e32 v6, 0x3fb8aa3b, v6
	v_sub_f32_e32 v5, v5, v2
	v_cvt_pk_bf16_f32 v86, v168, v169
	v_add_f32_e32 v3, v98, v3
	v_exp_f32_e32 v102, v6
	v_mul_f32_e32 v5, 0x3fb8aa3b, v5
	v_cvt_pk_bf16_f32 v87, v170, v171
	v_cvt_pk_bf16_f32 v88, v172, v173
	v_cvt_pk_bf16_f32 v89, v174, v175
	v_add_f32_e32 v3, v99, v3
	s_waitcnt vmcnt(13)
	v_mfma_f32_16x16x32_bf16 v[14:17], v[122:125], v[86:89], v[16:19]
	v_add_f32_e32 v3, v100, v3
	v_add_f32_e32 v3, v101, v3
	v_add_f32_e32 v3, v102, v3
	s_waitcnt vmcnt(12)
	v_mfma_f32_16x16x32_bf16 v[18:21], v[126:129], v[86:89], v[20:23]
	v_sub_f32_e32 v1, v1, v2
	v_mul_f32_e32 v1, 0x3fb8aa3b, v1
	v_sub_f32_e32 v0, v0, v2
	s_waitcnt vmcnt(10)
	v_mfma_f32_16x16x32_bf16 v[8:11], v[130:133], v[86:89], v[10:13]
	v_mul_f32_e32 v0, 0x3fb8aa3b, v0
	v_lshl_add_u64 v[60:61], v[60:61], 0, s[48:49]
	s_waitcnt vmcnt(6)
	v_mfma_f32_16x16x32_bf16 v[32:35], v[134:137], v[86:89], v[32:35]
	v_cvt_pk_bf16_f32 v86, v50, v176
	v_exp_f32_e32 v50, v5
	v_cvt_pk_bf16_f32 v87, v177, v178
	v_cvt_pk_bf16_f32 v88, v179, v180
	v_cvt_pk_bf16_f32 v89, v181, v182
	s_nop 0
	v_add_f32_e32 v5, v50, v3
	v_sub_f32_e32 v3, v4, v2
	v_mfma_f32_16x16x32_bf16 v[12:15], v[138:141], v[86:89], v[14:17]
	v_mul_f32_e32 v3, 0x3fb8aa3b, v3
	v_mfma_f32_16x16x32_bf16 v[6:9], v[36:39], v[86:89], v[8:11]
	v_exp_f32_e32 v36, v3
	v_exp_f32_e32 v37, v1
	v_exp_f32_e32 v38, v0
	v_mfma_f32_16x16x32_bf16 v[16:19], v[142:145], v[86:89], v[18:21]
	v_add_f32_e32 v4, v36, v5
	v_add_f32_e32 v4, v37, v4
	v_add_f32_e32 v39, v38, v4
	v_mfma_f32_16x16x32_bf16 v[20:23], v[40:43], v[86:89], v[32:35]
	v_cvt_pk_bf16_f32 v32, v183, v184
	v_cvt_pk_bf16_f32 v33, v185, v186
	v_cvt_pk_bf16_f32 v34, v187, v188
	v_cvt_pk_bf16_f32 v35, v156, v98
	s_nop 0
	v_mfma_f32_16x16x32_bf16 v[10:13], v[146:149], v[32:35], v[12:15]
	s_waitcnt vmcnt(5)
	v_mfma_f32_16x16x32_bf16 v[14:17], v[44:47], v[32:35], v[16:19]
	v_cvt_pk_bf16_f32 v18, v99, v100
	v_cvt_pk_bf16_f32 v19, v101, v102
	s_waitcnt vmcnt(4)
	v_mfma_f32_16x16x32_bf16 v[0:3], v[114:117], v[32:35], v[6:9]
	s_waitcnt vmcnt(3)
	v_mfma_f32_16x16x32_bf16 v[4:7], v[90:93], v[32:35], v[20:23]
	v_cvt_pk_bf16_f32 v20, v50, v36
	v_cvt_pk_bf16_f32 v21, v37, v38
	s_nop 0
	v_mfma_f32_16x16x32_bf16 v[8:11], v[150:153], v[18:21], v[10:13]
	s_nop 2
	ds_bpermute_b32 v12, v73, v39
	s_waitcnt vmcnt(1)
	v_mfma_f32_16x16x32_bf16 v[0:3], v[94:97], v[18:21], v[0:3]
	s_waitcnt lgkmcnt(0)
	v_add_f32_e32 v22, v39, v12
	v_mfma_f32_16x16x32_bf16 v[12:15], v[28:31], v[18:21], v[14:17]
	s_nop 2
	ds_bpermute_b32 v16, v74, v22
	s_waitcnt vmcnt(0)
	v_mfma_f32_16x16x32_bf16 v[4:7], v[24:27], v[18:21], v[4:7]
	s_waitcnt lgkmcnt(0)
	v_add_f32_e32 v16, v22, v16
	v_div_scale_f32 v17, s[0:1], v16, v16, 1.0
	v_rcp_f32_e32 v22, v17
	s_nop 0
	v_fma_f32 v18, -v17, v22, 1.0
	v_fmac_f32_e32 v22, v18, v22
	v_div_scale_f32 v18, vcc, 1.0, v16, 1.0
	v_mul_f32_e32 v19, v18, v22
	v_fma_f32 v20, -v17, v19, v18
	v_fmac_f32_e32 v19, v20, v22
	v_fma_f32 v17, -v17, v19, v18
	v_div_fmas_f32 v17, v17, v22, v19
	v_div_fixup_f32 v18, v17, v16, 1.0
	v_mul_f32_e32 v8, v18, v8
	v_mul_f32_e32 v9, v18, v9
	v_mul_f32_e32 v0, v18, v0
	v_mul_f32_e32 v1, v18, v1
	v_cvt_pk_bf16_f32 v8, v8, v9
	v_mul_f32_e32 v9, v18, v10
	v_cvt_pk_bf16_f32 v0, v0, v1
	v_mul_f32_e32 v1, v18, v2
	v_lshl_add_u64 v[16:17], s[70:71], 0, v[62:63]
	v_mul_f32_e32 v10, v18, v11
	v_cvt_pk_bf16_f32 v9, v9, v10
	v_mul_f32_e32 v2, v18, v3
	v_cvt_pk_bf16_f32 v1, v1, v2
	global_store_dwordx2 v[16:17], v[8:9], off offset:-64
	v_mul_f32_e32 v8, v18, v12
	v_mul_f32_e32 v9, v18, v13
	global_store_dwordx2 v[16:17], v[0:1], off
	v_mul_f32_e32 v0, v18, v4
	v_mul_f32_e32 v1, v18, v5
	v_cvt_pk_bf16_f32 v8, v8, v9
	v_mul_f32_e32 v9, v18, v14
	v_cvt_pk_bf16_f32 v0, v0, v1
	v_mul_f32_e32 v1, v18, v6
	v_lshl_add_u64 v[62:63], v[62:63], 0, s[50:51]
	v_mul_f32_e32 v10, v18, v15
	v_cvt_pk_bf16_f32 v9, v9, v10
	global_store_dwordx2 v[16:17], v[8:9], off offset:-32
	v_mul_f32_e32 v2, v18, v7
	v_cvt_pk_bf16_f32 v1, v1, v2
	global_store_dwordx2 v[16:17], v[0:1], off offset:32
	s_cbranch_scc1 .LBB0_904
